# ph14 rotary loop processes 8 rows per iteration with all 24 loads in flight (was one row per iteration, loads waited on before its stores); differential-attention item tail: loads issued up front, 16-
# speedup vs baseline: 1.0421x; 1.0016x over previous
; #define GAS __attribute__((address_space(1)))
; DI unsigned pk2(float a, float b) { f32x2 v = {a, b}; bf2_t r = __builtin_convertvector(v, bf2_t); return __builtin_bit_cast(unsigned, r); }
; DI float bflo(unsigned w) { return __uint_as_float(w << 16); }
; DI float bfhi(unsigned w) { return __uint_as_float(w & 0xffff0000u); }
; __global__ void __launch_bounds__(256, 2) fwd_kernel(Params p) {
;     ...
;           ss += __shfl_xor(ss, 32);
;           const float rinv = rsqrtf(ss * (1.f / 128.f) + 1e-6f) * 0.8f;
;           const float* subg = pp->in[18];
; #pragma unroll
;           for (int t = 0; t < 4; ++t)
; #pragma unroll
;             for (int g = 0; g < 4; ++g) {
;               bf16_t* a = outp + 32 * t + 8 * g + 4 * h;
;               const u32x2 w = *(const GAS u32x2*)a;
;               const f32x4 g4 = *(const GAS f32x4*)(subg + 32 * t + 8 * g + 4 * h);
;               u32x2 o; o.x = pk2(bflo(w.x) * rinv * g4[0], bfhi(w.x) * rinv * g4[1]); o.y = pk2(bflo(w.y) * rinv * g4[2], bfhi(w.y) * rinv * g4[3]);
;               *(GAS u32x2*)a = o;
;             }
.LBB0_28:
	ds_bpermute_b32 v0, v115, v98
	s_mov_b32 s10, 0x800000
	s_load_dwordx2 s[12:13], s[8:9], 0x90
	s_waitcnt lgkmcnt(0)
	v_add_f32_e32 v0, v98, v0
	v_fmamk_f32 v0, v0, 0x3c000000, v186
	v_cmp_gt_f32_e32 vcc, s10, v0
	v_mul_f32_e32 v2, 0x4b800000, v0
	v_readlane_b32 s10, v252, 12
	v_cndmask_b32_e32 v0, v0, v2, vcc
	v_rsq_f32_e32 v0, v0
	s_add_i32 s22, s22, s10
	v_readlane_b32 s10, v252, 14
	s_cmp_ge_i32 s22, s10
	v_mul_f32_e32 v2, 0x45800000, v0
	v_cndmask_b32_e32 v0, v0, v2, vcc
	v_lshlrev_b32_e32 v2, 2, v112
	v_mul_f32_e32 v0, 0x3f4ccccd, v0
	v_mbcnt_lo_u32_b32 v14, -1, 0
	v_mbcnt_hi_u32_b32 v14, -1, v14
	v_and_b32_e32 v14, 32, v14
	v_lshrrev_b32_e32 v14, 2, v14
	v_mov_b32_e32 v15, 0
	v_lshl_add_u64 v[12:13], v[146:147], 0, v[14:15]
	global_load_dwordx4 v[16:19], v[12:13], off
	global_load_dwordx4 v[48:51], v2, s[12:13]
	global_load_dwordx4 v[52:55], v2, s[12:13] offset:32
	global_load_dwordx4 v[20:23], v[12:13], off offset:32
	global_load_dwordx4 v[56:59], v2, s[12:13] offset:64
	global_load_dwordx4 v[60:63], v2, s[12:13] offset:96
	global_load_dwordx4 v[24:27], v[12:13], off offset:64
	global_load_dwordx4 v[64:67], v2, s[12:13] offset:128
	global_load_dwordx4 v[68:71], v2, s[12:13] offset:160
	global_load_dwordx4 v[28:31], v[12:13], off offset:96
	global_load_dwordx4 v[72:75], v2, s[12:13] offset:192
	global_load_dwordx4 v[76:79], v2, s[12:13] offset:224
	global_load_dwordx4 v[32:35], v[12:13], off offset:128
	global_load_dwordx4 v[80:83], v2, s[12:13] offset:256
	global_load_dwordx4 v[84:87], v2, s[12:13] offset:288
	global_load_dwordx4 v[36:39], v[12:13], off offset:160
	global_load_dwordx4 v[88:91], v2, s[12:13] offset:320
	global_load_dwordx4 v[92:95], v2, s[12:13] offset:352
	global_load_dwordx4 v[40:43], v[12:13], off offset:192
	global_load_dwordx4 v[96:99], v2, s[12:13] offset:384
	global_load_dwordx4 v[100:103], v2, s[12:13] offset:416
	global_load_dwordx4 v[44:47], v[12:13], off offset:224
	global_load_dwordx4 v[104:107], v2, s[12:13] offset:448
	global_load_dwordx4 v[108:111], v2, s[12:13] offset:480
	s_waitcnt vmcnt(21)
	v_permlane32_swap_b32_e32 v16, v18
	v_permlane32_swap_b32_e32 v17, v19
	v_lshlrev_b32_e32 v8, 16, v16
	v_and_b32_e32 v9, 0xffff0000, v16
	v_lshlrev_b32_e32 v10, 16, v17
	v_and_b32_e32 v11, 0xffff0000, v17
	v_mul_f32_e32 v8, v0, v8
	v_mul_f32_e32 v9, v0, v9
	v_mul_f32_e32 v10, v0, v10
	v_mul_f32_e32 v11, v0, v11
	v_mul_f32_e32 v8, v48, v8
	v_mul_f32_e32 v9, v49, v9
	v_mul_f32_e32 v10, v50, v10
	v_mul_f32_e32 v11, v51, v11
	v_cvt_pk_bf16_f32 v4, v8, v9
	v_cvt_pk_bf16_f32 v5, v10, v11
	v_lshlrev_b32_e32 v8, 16, v18
	v_and_b32_e32 v9, 0xffff0000, v18
	v_lshlrev_b32_e32 v10, 16, v19
	v_and_b32_e32 v11, 0xffff0000, v19
	v_mul_f32_e32 v8, v0, v8
	v_mul_f32_e32 v9, v0, v9
	v_mul_f32_e32 v10, v0, v10
	v_mul_f32_e32 v11, v0, v11
	v_mul_f32_e32 v8, v52, v8
	v_mul_f32_e32 v9, v53, v9
	v_mul_f32_e32 v10, v54, v10
	v_mul_f32_e32 v11, v55, v11
	v_cvt_pk_bf16_f32 v6, v8, v9
	v_cvt_pk_bf16_f32 v7, v10, v11
	s_nop 1
	v_permlane32_swap_b32_e32 v4, v6
	v_permlane32_swap_b32_e32 v5, v7
	global_store_dwordx4 v[12:13], v[4:7], off
	s_waitcnt vmcnt(19)
	v_permlane32_swap_b32_e32 v20, v22
	v_permlane32_swap_b32_e32 v21, v23
	v_lshlrev_b32_e32 v8, 16, v20
	v_and_b32_e32 v9, 0xffff0000, v20
	v_lshlrev_b32_e32 v10, 16, v21
	v_and_b32_e32 v11, 0xffff0000, v21
	v_mul_f32_e32 v8, v0, v8
	v_mul_f32_e32 v9, v0, v9
	v_mul_f32_e32 v10, v0, v10
	v_mul_f32_e32 v11, v0, v11
	v_mul_f32_e32 v8, v56, v8
	v_mul_f32_e32 v9, v57, v9
	v_mul_f32_e32 v10, v58, v10
	v_mul_f32_e32 v11, v59, v11
	v_cvt_pk_bf16_f32 v4, v8, v9
	v_cvt_pk_bf16_f32 v5, v10, v11
	v_lshlrev_b32_e32 v8, 16, v22
	v_and_b32_e32 v9, 0xffff0000, v22
	v_lshlrev_b32_e32 v10, 16, v23
	v_and_b32_e32 v11, 0xffff0000, v23
	v_mul_f32_e32 v8, v0, v8
	v_mul_f32_e32 v9, v0, v9
	v_mul_f32_e32 v10, v0, v10
	v_mul_f32_e32 v11, v0, v11
	v_mul_f32_e32 v8, v60, v8
	v_mul_f32_e32 v9, v61, v9
	v_mul_f32_e32 v10, v62, v10
	v_mul_f32_e32 v11, v63, v11
	v_cvt_pk_bf16_f32 v6, v8, v9
	v_cvt_pk_bf16_f32 v7, v10, v11
	s_nop 1
	v_permlane32_swap_b32_e32 v4, v6
	v_permlane32_swap_b32_e32 v5, v7
	global_store_dwordx4 v[12:13], v[4:7], off offset:32
	s_waitcnt vmcnt(17)
	v_permlane32_swap_b32_e32 v24, v26
	v_permlane32_swap_b32_e32 v25, v27
	v_lshlrev_b32_e32 v8, 16, v24
	v_and_b32_e32 v9, 0xffff0000, v24
	v_lshlrev_b32_e32 v10, 16, v25
	v_and_b32_e32 v11, 0xffff0000, v25
	v_mul_f32_e32 v8, v0, v8
	v_mul_f32_e32 v9, v0, v9
	v_mul_f32_e32 v10, v0, v10
	v_mul_f32_e32 v11, v0, v11
	v_mul_f32_e32 v8, v64, v8
	v_mul_f32_e32 v9, v65, v9
	v_mul_f32_e32 v10, v66, v10
	v_mul_f32_e32 v11, v67, v11
	v_cvt_pk_bf16_f32 v4, v8, v9
	v_cvt_pk_bf16_f32 v5, v10, v11
	v_lshlrev_b32_e32 v8, 16, v26
	v_and_b32_e32 v9, 0xffff0000, v26
	v_lshlrev_b32_e32 v10, 16, v27
	v_and_b32_e32 v11, 0xffff0000, v27
	v_mul_f32_e32 v8, v0, v8
	v_mul_f32_e32 v9, v0, v9
	v_mul_f32_e32 v10, v0, v10
	v_mul_f32_e32 v11, v0, v11
	v_mul_f32_e32 v8, v68, v8
	v_mul_f32_e32 v9, v69, v9
	v_mul_f32_e32 v10, v70, v10
	v_mul_f32_e32 v11, v71, v11
	v_cvt_pk_bf16_f32 v6, v8, v9
	v_cvt_pk_bf16_f32 v7, v10, v11
	s_nop 1
	v_permlane32_swap_b32_e32 v4, v6
	v_permlane32_swap_b32_e32 v5, v7
	global_store_dwordx4 v[12:13], v[4:7], off offset:64
	s_waitcnt vmcnt(15)
; #define GAS __attribute__((address_space(1)))
; DI unsigned pk2(float a, float b) { f32x2 v = {a, b}; bf2_t r = __builtin_convertvector(v, bf2_t); return __builtin_bit_cast(unsigned, r); }
; DI float bflo(unsigned w) { return __uint_as_float(w << 16); }
; DI float bfhi(unsigned w) { return __uint_as_float(w & 0xffff0000u); }
; __global__ void __launch_bounds__(256, 2) fwd_kernel(Params p) {
;     ...
; #pragma unroll
;           for (int t = 0; t < 4; ++t)
; #pragma unroll
;             for (int g = 0; g < 4; ++g) {
;               bf16_t* a = outp + 32 * t + 8 * g + 4 * h;
;               const u32x2 w = *(const GAS u32x2*)a;
;               const f32x4 g4 = *(const GAS f32x4*)(subg + 32 * t + 8 * g + 4 * h);
;               u32x2 o; o.x = pk2(bflo(w.x) * rinv * g4[0], bfhi(w.x) * rinv * g4[1]); o.y = pk2(bflo(w.y) * rinv * g4[2], bfhi(w.y) * rinv * g4[3]);
;               *(GAS u32x2*)a = o;
;             }
	v_permlane32_swap_b32_e32 v28, v30
	v_permlane32_swap_b32_e32 v29, v31
	v_lshlrev_b32_e32 v8, 16, v28
	v_and_b32_e32 v9, 0xffff0000, v28
	v_lshlrev_b32_e32 v10, 16, v29
	v_and_b32_e32 v11, 0xffff0000, v29
	v_mul_f32_e32 v8, v0, v8
	v_mul_f32_e32 v9, v0, v9
	v_mul_f32_e32 v10, v0, v10
	v_mul_f32_e32 v11, v0, v11
	v_mul_f32_e32 v8, v72, v8
	v_mul_f32_e32 v9, v73, v9
	v_mul_f32_e32 v10, v74, v10
	v_mul_f32_e32 v11, v75, v11
	v_cvt_pk_bf16_f32 v4, v8, v9
	v_cvt_pk_bf16_f32 v5, v10, v11
	v_lshlrev_b32_e32 v8, 16, v30
	v_and_b32_e32 v9, 0xffff0000, v30
	v_lshlrev_b32_e32 v10, 16, v31
	v_and_b32_e32 v11, 0xffff0000, v31
	v_mul_f32_e32 v8, v0, v8
	v_mul_f32_e32 v9, v0, v9
	v_mul_f32_e32 v10, v0, v10
	v_mul_f32_e32 v11, v0, v11
	v_mul_f32_e32 v8, v76, v8
	v_mul_f32_e32 v9, v77, v9
	v_mul_f32_e32 v10, v78, v10
	v_mul_f32_e32 v11, v79, v11
	v_cvt_pk_bf16_f32 v6, v8, v9
	v_cvt_pk_bf16_f32 v7, v10, v11
	s_nop 1
	v_permlane32_swap_b32_e32 v4, v6
	v_permlane32_swap_b32_e32 v5, v7
	global_store_dwordx4 v[12:13], v[4:7], off offset:96
	s_waitcnt vmcnt(13)
	v_permlane32_swap_b32_e32 v32, v34
	v_permlane32_swap_b32_e32 v33, v35
	v_lshlrev_b32_e32 v8, 16, v32
	v_and_b32_e32 v9, 0xffff0000, v32
	v_lshlrev_b32_e32 v10, 16, v33
	v_and_b32_e32 v11, 0xffff0000, v33
	v_mul_f32_e32 v8, v0, v8
	v_mul_f32_e32 v9, v0, v9
	v_mul_f32_e32 v10, v0, v10
	v_mul_f32_e32 v11, v0, v11
	v_mul_f32_e32 v8, v80, v8
	v_mul_f32_e32 v9, v81, v9
	v_mul_f32_e32 v10, v82, v10
	v_mul_f32_e32 v11, v83, v11
	v_cvt_pk_bf16_f32 v4, v8, v9
	v_cvt_pk_bf16_f32 v5, v10, v11
	v_lshlrev_b32_e32 v8, 16, v34
	v_and_b32_e32 v9, 0xffff0000, v34
	v_lshlrev_b32_e32 v10, 16, v35
	v_and_b32_e32 v11, 0xffff0000, v35
	v_mul_f32_e32 v8, v0, v8
	v_mul_f32_e32 v9, v0, v9
	v_mul_f32_e32 v10, v0, v10
	v_mul_f32_e32 v11, v0, v11
	v_mul_f32_e32 v8, v84, v8
	v_mul_f32_e32 v9, v85, v9
	v_mul_f32_e32 v10, v86, v10
	v_mul_f32_e32 v11, v87, v11
	v_cvt_pk_bf16_f32 v6, v8, v9
	v_cvt_pk_bf16_f32 v7, v10, v11
	s_nop 1
	v_permlane32_swap_b32_e32 v4, v6
	v_permlane32_swap_b32_e32 v5, v7
	global_store_dwordx4 v[12:13], v[4:7], off offset:128
	s_waitcnt vmcnt(11)
	v_permlane32_swap_b32_e32 v36, v38
	v_permlane32_swap_b32_e32 v37, v39
	v_lshlrev_b32_e32 v8, 16, v36
	v_and_b32_e32 v9, 0xffff0000, v36
	v_lshlrev_b32_e32 v10, 16, v37
	v_and_b32_e32 v11, 0xffff0000, v37
	v_mul_f32_e32 v8, v0, v8
	v_mul_f32_e32 v9, v0, v9
	v_mul_f32_e32 v10, v0, v10
	v_mul_f32_e32 v11, v0, v11
	v_mul_f32_e32 v8, v88, v8
	v_mul_f32_e32 v9, v89, v9
	v_mul_f32_e32 v10, v90, v10
	v_mul_f32_e32 v11, v91, v11
	v_cvt_pk_bf16_f32 v4, v8, v9
	v_cvt_pk_bf16_f32 v5, v10, v11
	v_lshlrev_b32_e32 v8, 16, v38
	v_and_b32_e32 v9, 0xffff0000, v38
	v_lshlrev_b32_e32 v10, 16, v39
	v_and_b32_e32 v11, 0xffff0000, v39
	v_mul_f32_e32 v8, v0, v8
	v_mul_f32_e32 v9, v0, v9
	v_mul_f32_e32 v10, v0, v10
	v_mul_f32_e32 v11, v0, v11
	v_mul_f32_e32 v8, v92, v8
	v_mul_f32_e32 v9, v93, v9
	v_mul_f32_e32 v10, v94, v10
	v_mul_f32_e32 v11, v95, v11
	v_cvt_pk_bf16_f32 v6, v8, v9
	v_cvt_pk_bf16_f32 v7, v10, v11
	s_nop 1
	v_permlane32_swap_b32_e32 v4, v6
	v_permlane32_swap_b32_e32 v5, v7
	global_store_dwordx4 v[12:13], v[4:7], off offset:160
	s_waitcnt vmcnt(9)
	v_permlane32_swap_b32_e32 v40, v42
	v_permlane32_swap_b32_e32 v41, v43
	v_lshlrev_b32_e32 v8, 16, v40
	v_and_b32_e32 v9, 0xffff0000, v40
	v_lshlrev_b32_e32 v10, 16, v41
	v_and_b32_e32 v11, 0xffff0000, v41
	v_mul_f32_e32 v8, v0, v8
	v_mul_f32_e32 v9, v0, v9
	v_mul_f32_e32 v10, v0, v10
	v_mul_f32_e32 v11, v0, v11
	v_mul_f32_e32 v8, v96, v8
	v_mul_f32_e32 v9, v97, v9
	v_mul_f32_e32 v10, v98, v10
	v_mul_f32_e32 v11, v99, v11
	v_cvt_pk_bf16_f32 v4, v8, v9
	v_cvt_pk_bf16_f32 v5, v10, v11
	v_lshlrev_b32_e32 v8, 16, v42
	v_and_b32_e32 v9, 0xffff0000, v42
	v_lshlrev_b32_e32 v10, 16, v43
	v_and_b32_e32 v11, 0xffff0000, v43
	v_mul_f32_e32 v8, v0, v8
	v_mul_f32_e32 v9, v0, v9
	v_mul_f32_e32 v10, v0, v10
	v_mul_f32_e32 v11, v0, v11
	v_mul_f32_e32 v8, v100, v8
	v_mul_f32_e32 v9, v101, v9
	v_mul_f32_e32 v10, v102, v10
	v_mul_f32_e32 v11, v103, v11
	v_cvt_pk_bf16_f32 v6, v8, v9
	v_cvt_pk_bf16_f32 v7, v10, v11
	s_nop 1
	v_permlane32_swap_b32_e32 v4, v6
	v_permlane32_swap_b32_e32 v5, v7
	global_store_dwordx4 v[12:13], v[4:7], off offset:192
	s_waitcnt vmcnt(7)
	v_permlane32_swap_b32_e32 v44, v46
	v_permlane32_swap_b32_e32 v45, v47
	v_lshlrev_b32_e32 v8, 16, v44
	v_and_b32_e32 v9, 0xffff0000, v44
	v_lshlrev_b32_e32 v10, 16, v45
	v_and_b32_e32 v11, 0xffff0000, v45
	v_mul_f32_e32 v8, v0, v8
	v_mul_f32_e32 v9, v0, v9
	v_mul_f32_e32 v10, v0, v10
	v_mul_f32_e32 v11, v0, v11
	v_mul_f32_e32 v8, v104, v8
	v_mul_f32_e32 v9, v105, v9
	v_mul_f32_e32 v10, v106, v10
	v_mul_f32_e32 v11, v107, v11
	v_cvt_pk_bf16_f32 v4, v8, v9
	v_cvt_pk_bf16_f32 v5, v10, v11
	v_lshlrev_b32_e32 v8, 16, v46
	v_and_b32_e32 v9, 0xffff0000, v46
	v_lshlrev_b32_e32 v10, 16, v47
	v_and_b32_e32 v11, 0xffff0000, v47
	v_mul_f32_e32 v8, v0, v8
	v_mul_f32_e32 v9, v0, v9
	v_mul_f32_e32 v10, v0, v10
	v_mul_f32_e32 v11, v0, v11
	v_mul_f32_e32 v8, v108, v8
	v_mul_f32_e32 v9, v109, v9
	v_mul_f32_e32 v10, v110, v10
	v_mul_f32_e32 v11, v111, v11
	v_cvt_pk_bf16_f32 v6, v8, v9
	v_cvt_pk_bf16_f32 v7, v10, v11
	s_nop 1
	v_permlane32_swap_b32_e32 v4, v6
	v_permlane32_swap_b32_e32 v5, v7
	global_store_dwordx4 v[12:13], v[4:7], off offset:224
	s_cbranch_scc1 .LBB0_53

; DI float bf2f(unsigned short v) { return __uint_as_float(((unsigned)v) << 16); }
; DI unsigned short f2bf(float x) { return (unsigned short)(pk2(x, 0.f) & 0xffffu); }
; __global__ void __launch_bounds__(256, 2) fwd_kernel(Params p) {
;     ...
;       for (int row = gw; row < NL; row += NW) {
;         const int t = row & 2047, grp = lane >> 5, ii = lane & 31;
;         bf16_t* a = P + (size_t)row * PLD + 512 + grp * 64 + ii;
;         const f32x2 cs = CS64[t * 32 + ii];
;         const float x1 = bf2f(a[0]), x2 = bf2f(a[32]);
;         a[0] = f2bf(x1 * cs.x - x2 * cs.y); a[32] = f2bf(x1 * cs.y + x2 * cs.x);
;       }
.LBB0_206:
	v_mov_b32_e32 v242, v2
	v_mov_b32_e32 v243, v3
	s_and_b32 s10, s20, 0xffe0
	v_or_b32_e32 v0, s10, v4
	v_lshlrev_b32_e32 v0, 3, v0
	global_load_ushort v226, v[2:3], off
	global_load_ushort v234, v[2:3], off offset:64
	v_lshl_add_u64 v[6:7], s[18:19], 0, v[0:1]
	global_load_dwordx2 v[10:11], v[6:7], off
	s_add_i32 s21, s21, s22
	s_add_i32 s20, s20, s23
	v_lshl_add_u64 v[2:3], v[2:3], 0, s[28:29]
	s_and_b32 s10, s20, 0xffe0
	v_or_b32_e32 v0, s10, v4
	v_lshlrev_b32_e32 v0, 3, v0
	global_load_ushort v227, v[2:3], off
	global_load_ushort v235, v[2:3], off offset:64
	v_lshl_add_u64 v[6:7], s[18:19], 0, v[0:1]
	global_load_dwordx2 v[12:13], v[6:7], off
	s_add_i32 s21, s21, s22
	s_add_i32 s20, s20, s23
	v_lshl_add_u64 v[2:3], v[2:3], 0, s[28:29]
	s_and_b32 s10, s20, 0xffe0
	v_or_b32_e32 v0, s10, v4
	v_lshlrev_b32_e32 v0, 3, v0
	global_load_ushort v228, v[2:3], off
	global_load_ushort v236, v[2:3], off offset:64
	v_lshl_add_u64 v[6:7], s[18:19], 0, v[0:1]
	global_load_dwordx2 v[14:15], v[6:7], off
	s_add_i32 s21, s21, s22
	s_add_i32 s20, s20, s23
	v_lshl_add_u64 v[2:3], v[2:3], 0, s[28:29]
	s_and_b32 s10, s20, 0xffe0
	v_or_b32_e32 v0, s10, v4
	v_lshlrev_b32_e32 v0, 3, v0
	global_load_ushort v229, v[2:3], off
	global_load_ushort v237, v[2:3], off offset:64
	v_lshl_add_u64 v[6:7], s[18:19], 0, v[0:1]
	global_load_dwordx2 v[16:17], v[6:7], off
	s_add_i32 s21, s21, s22
	s_add_i32 s20, s20, s23
	v_lshl_add_u64 v[2:3], v[2:3], 0, s[28:29]
	s_and_b32 s10, s20, 0xffe0
	v_or_b32_e32 v0, s10, v4
	v_lshlrev_b32_e32 v0, 3, v0
	global_load_ushort v230, v[2:3], off
	global_load_ushort v238, v[2:3], off offset:64
	v_lshl_add_u64 v[6:7], s[18:19], 0, v[0:1]
	global_load_dwordx2 v[18:19], v[6:7], off
	s_add_i32 s21, s21, s22
	s_add_i32 s20, s20, s23
	v_lshl_add_u64 v[2:3], v[2:3], 0, s[28:29]
	s_and_b32 s10, s20, 0xffe0
	v_or_b32_e32 v0, s10, v4
	v_lshlrev_b32_e32 v0, 3, v0
	global_load_ushort v231, v[2:3], off
	global_load_ushort v239, v[2:3], off offset:64
	v_lshl_add_u64 v[6:7], s[18:19], 0, v[0:1]
	global_load_dwordx2 v[20:21], v[6:7], off
	s_add_i32 s21, s21, s22
	s_add_i32 s20, s20, s23
	v_lshl_add_u64 v[2:3], v[2:3], 0, s[28:29]
	s_and_b32 s10, s20, 0xffe0
	v_or_b32_e32 v0, s10, v4
	v_lshlrev_b32_e32 v0, 3, v0
	global_load_ushort v232, v[2:3], off
	global_load_ushort v240, v[2:3], off offset:64
	v_lshl_add_u64 v[6:7], s[18:19], 0, v[0:1]
	global_load_dwordx2 v[22:23], v[6:7], off
	s_add_i32 s21, s21, s22
	s_add_i32 s20, s20, s23
	v_lshl_add_u64 v[2:3], v[2:3], 0, s[28:29]
	s_and_b32 s10, s20, 0xffe0
	v_or_b32_e32 v0, s10, v4
	v_lshlrev_b32_e32 v0, 3, v0
	global_load_ushort v233, v[2:3], off
	global_load_ushort v241, v[2:3], off offset:64
	v_lshl_add_u64 v[6:7], s[18:19], 0, v[0:1]
	global_load_dwordx2 v[24:25], v[6:7], off
	s_add_i32 s21, s21, s22
	s_add_i32 s20, s20, s23
	v_lshl_add_u64 v[2:3], v[2:3], 0, s[28:29]
	s_waitcnt vmcnt(21)
	v_lshlrev_b32_e32 v0, 16, v226
	v_lshlrev_b32_e32 v5, 16, v234
	v_mul_f32_e32 v8, v11, v5
	v_mul_f32_e32 v5, v10, v5
	v_fma_f32 v6, v10, v0, -v8
	v_fmac_f32_e32 v5, v11, v0
	v_cvt_pk_bf16_f32 v0, v6, s0
	v_cvt_pk_bf16_f32 v5, v5, s0
	global_store_short v[242:243], v0, off
	global_store_short v[242:243], v5, off offset:64
	v_lshl_add_u64 v[242:243], v[242:243], 0, s[28:29]
	s_waitcnt vmcnt(20)
	v_lshlrev_b32_e32 v0, 16, v227
	v_lshlrev_b32_e32 v5, 16, v235
	v_mul_f32_e32 v8, v13, v5
	v_mul_f32_e32 v5, v12, v5
	v_fma_f32 v6, v12, v0, -v8
	v_fmac_f32_e32 v5, v13, v0
	v_cvt_pk_bf16_f32 v0, v6, s0
	v_cvt_pk_bf16_f32 v5, v5, s0
	global_store_short v[242:243], v0, off
	global_store_short v[242:243], v5, off offset:64
	v_lshl_add_u64 v[242:243], v[242:243], 0, s[28:29]
	s_waitcnt vmcnt(19)
	v_lshlrev_b32_e32 v0, 16, v228
	v_lshlrev_b32_e32 v5, 16, v236
	v_mul_f32_e32 v8, v15, v5
	v_mul_f32_e32 v5, v14, v5
	v_fma_f32 v6, v14, v0, -v8
	v_fmac_f32_e32 v5, v15, v0
	v_cvt_pk_bf16_f32 v0, v6, s0
	v_cvt_pk_bf16_f32 v5, v5, s0
	global_store_short v[242:243], v0, off
	global_store_short v[242:243], v5, off offset:64
	v_lshl_add_u64 v[242:243], v[242:243], 0, s[28:29]
	s_waitcnt vmcnt(18)
	v_lshlrev_b32_e32 v0, 16, v229
	v_lshlrev_b32_e32 v5, 16, v237
	v_mul_f32_e32 v8, v17, v5
	v_mul_f32_e32 v5, v16, v5
	v_fma_f32 v6, v16, v0, -v8
	v_fmac_f32_e32 v5, v17, v0
	v_cvt_pk_bf16_f32 v0, v6, s0
	v_cvt_pk_bf16_f32 v5, v5, s0
	global_store_short v[242:243], v0, off
	global_store_short v[242:243], v5, off offset:64
	v_lshl_add_u64 v[242:243], v[242:243], 0, s[28:29]
	s_waitcnt vmcnt(17)
	v_lshlrev_b32_e32 v0, 16, v230
	v_lshlrev_b32_e32 v5, 16, v238
	v_mul_f32_e32 v8, v19, v5
	v_mul_f32_e32 v5, v18, v5
	v_fma_f32 v6, v18, v0, -v8
	v_fmac_f32_e32 v5, v19, v0
	v_cvt_pk_bf16_f32 v0, v6, s0
	v_cvt_pk_bf16_f32 v5, v5, s0
	global_store_short v[242:243], v0, off
	global_store_short v[242:243], v5, off offset:64
	v_lshl_add_u64 v[242:243], v[242:243], 0, s[28:29]
	s_waitcnt vmcnt(16)
	v_lshlrev_b32_e32 v0, 16, v231
	v_lshlrev_b32_e32 v5, 16, v239
	v_mul_f32_e32 v8, v21, v5
	v_mul_f32_e32 v5, v20, v5
	v_fma_f32 v6, v20, v0, -v8
	v_fmac_f32_e32 v5, v21, v0
	v_cvt_pk_bf16_f32 v0, v6, s0
	v_cvt_pk_bf16_f32 v5, v5, s0
	global_store_short v[242:243], v0, off
	global_store_short v[242:243], v5, off offset:64
	v_lshl_add_u64 v[242:243], v[242:243], 0, s[28:29]
	s_waitcnt vmcnt(15)
	v_lshlrev_b32_e32 v0, 16, v232
	v_lshlrev_b32_e32 v5, 16, v240
	v_mul_f32_e32 v8, v23, v5
	v_mul_f32_e32 v5, v22, v5
	v_fma_f32 v6, v22, v0, -v8
	v_fmac_f32_e32 v5, v23, v0
	v_cvt_pk_bf16_f32 v0, v6, s0
	v_cvt_pk_bf16_f32 v5, v5, s0
	global_store_short v[242:243], v0, off
	global_store_short v[242:243], v5, off offset:64
	v_lshl_add_u64 v[242:243], v[242:243], 0, s[28:29]
	s_waitcnt vmcnt(14)
	v_lshlrev_b32_e32 v0, 16, v233
	v_lshlrev_b32_e32 v5, 16, v241
	v_mul_f32_e32 v8, v25, v5
	v_mul_f32_e32 v5, v24, v5
	v_fma_f32 v6, v24, v0, -v8
	v_fmac_f32_e32 v5, v25, v0
	v_cvt_pk_bf16_f32 v0, v6, s0
	v_cvt_pk_bf16_f32 v5, v5, s0
	global_store_short v[242:243], v0, off
	global_store_short v[242:243], v5, off offset:64
	v_lshl_add_u64 v[242:243], v[242:243], 0, s[28:29]
	s_cmp_gt_i32 s21, 0xffff
	s_cbranch_scc0 .LBB0_206
